# PEER token loop: issue priority 3 in the per-token serial sections, phase priority inside the memory-bound gather loop
# speedup vs baseline: 1.2042x; 1.0086x over previous
.LBB0_864:
	s_setprio 3
	s_mul_i32 s0, s19, s97
	v_add_u32_e32 v0, s0, v130
	v_cmp_gt_i32_e32 vcc, s51, v0
	s_or_b64 s[28:29], s[28:29], exec
	s_and_saveexec_b64 s[38:39], vcc
	s_cbranch_execz .LBB0_863
	s_mov_b32 s20, 0
	v_mov_b32_e32 v2, v198
	v_mov_b32_e32 v3, v200
	s_branch .LBB0_867

.LBB0_869:
	ds_read2st64_b32 v[4:5], v220 offset0:12 offset1:13
	ds_read2st64_b32 v[6:7], v220 offset0:14 offset1:15
	v_mov_b32_e32 v10, 0
	v_mov_b32_e32 v11, 0
	s_mov_b32 s0, 0
	s_waitcnt lgkmcnt(0)
	v_lshrrev_b32_e32 v8, 11, v4
	v_lshrrev_b32_e32 v9, 11, v5
	v_cmp_eq_u32_e64 s[42:43], 0, v8
	v_cmp_eq_u32_e64 s[100:101], 0, v9
	s_bcnt1_i32_b64 s1, s[42:43]
	s_bcnt1_i32_b64 s41, s[100:101]
	v_mbcnt_lo_u32_b32 v12, s42, 0
	v_mbcnt_hi_u32_b32 v12, s43, v12
	v_mbcnt_lo_u32_b32 v13, s100, 0
	v_mbcnt_hi_u32_b32 v13, s101, v13
	s_add_i32 s98, s0, s1
	v_add_u32_e32 v12, s0, v12
	v_add_u32_e32 v13, s98, v13
	v_cndmask_b32_e64 v10, v10, v12, s[42:43]
	v_cndmask_b32_e64 v11, v11, v13, s[100:101]
	s_add_i32 s0, s98, s41
	v_cmp_eq_u32_e64 s[42:43], 1, v8
	v_cmp_eq_u32_e64 s[100:101], 1, v9
	s_bcnt1_i32_b64 s1, s[42:43]
	s_bcnt1_i32_b64 s41, s[100:101]
	v_mbcnt_lo_u32_b32 v12, s42, 0
	v_mbcnt_hi_u32_b32 v12, s43, v12
	v_mbcnt_lo_u32_b32 v13, s100, 0
	v_mbcnt_hi_u32_b32 v13, s101, v13
	s_add_i32 s98, s0, s1
	v_add_u32_e32 v12, s0, v12
	v_add_u32_e32 v13, s98, v13
	v_cndmask_b32_e64 v10, v10, v12, s[42:43]
	v_cndmask_b32_e64 v11, v11, v13, s[100:101]
	s_add_i32 s0, s98, s41
	v_cmp_eq_u32_e64 s[42:43], 2, v8
	v_cmp_eq_u32_e64 s[100:101], 2, v9
	s_bcnt1_i32_b64 s1, s[42:43]
	s_bcnt1_i32_b64 s41, s[100:101]
	v_mbcnt_lo_u32_b32 v12, s42, 0
	v_mbcnt_hi_u32_b32 v12, s43, v12
	v_mbcnt_lo_u32_b32 v13, s100, 0
	v_mbcnt_hi_u32_b32 v13, s101, v13
	s_add_i32 s98, s0, s1
	v_add_u32_e32 v12, s0, v12
	v_add_u32_e32 v13, s98, v13
	v_cndmask_b32_e64 v10, v10, v12, s[42:43]
	v_cndmask_b32_e64 v11, v11, v13, s[100:101]
	s_add_i32 s0, s98, s41
	v_cmp_eq_u32_e64 s[42:43], 3, v8
	v_cmp_eq_u32_e64 s[100:101], 3, v9
	s_bcnt1_i32_b64 s1, s[42:43]
	s_bcnt1_i32_b64 s41, s[100:101]
	v_mbcnt_lo_u32_b32 v12, s42, 0
	v_mbcnt_hi_u32_b32 v12, s43, v12
	v_mbcnt_lo_u32_b32 v13, s100, 0
	v_mbcnt_hi_u32_b32 v13, s101, v13
	s_add_i32 s98, s0, s1
	v_add_u32_e32 v12, s0, v12
	v_add_u32_e32 v13, s98, v13
	v_cndmask_b32_e64 v10, v10, v12, s[42:43]
	v_cndmask_b32_e64 v11, v11, v13, s[100:101]
	s_add_i32 s0, s98, s41
	v_cmp_eq_u32_e64 s[42:43], 4, v8
	v_cmp_eq_u32_e64 s[100:101], 4, v9
	s_bcnt1_i32_b64 s1, s[42:43]
	s_bcnt1_i32_b64 s41, s[100:101]
	v_mbcnt_lo_u32_b32 v12, s42, 0
	v_mbcnt_hi_u32_b32 v12, s43, v12
	v_mbcnt_lo_u32_b32 v13, s100, 0
	v_mbcnt_hi_u32_b32 v13, s101, v13
	s_add_i32 s98, s0, s1
	v_add_u32_e32 v12, s0, v12
	v_add_u32_e32 v13, s98, v13
	v_cndmask_b32_e64 v10, v10, v12, s[42:43]
	v_cndmask_b32_e64 v11, v11, v13, s[100:101]
	s_add_i32 s0, s98, s41
	v_cmp_eq_u32_e64 s[42:43], 5, v8
	v_cmp_eq_u32_e64 s[100:101], 5, v9
	s_bcnt1_i32_b64 s1, s[42:43]
	s_bcnt1_i32_b64 s41, s[100:101]
	v_mbcnt_lo_u32_b32 v12, s42, 0
	v_mbcnt_hi_u32_b32 v12, s43, v12
	v_mbcnt_lo_u32_b32 v13, s100, 0
	v_mbcnt_hi_u32_b32 v13, s101, v13
	s_add_i32 s98, s0, s1
	v_add_u32_e32 v12, s0, v12
	v_add_u32_e32 v13, s98, v13
	v_cndmask_b32_e64 v10, v10, v12, s[42:43]
	v_cndmask_b32_e64 v11, v11, v13, s[100:101]
	s_add_i32 s0, s98, s41
	v_cmp_eq_u32_e64 s[42:43], 6, v8
	v_cmp_eq_u32_e64 s[100:101], 6, v9
	s_bcnt1_i32_b64 s1, s[42:43]
	s_bcnt1_i32_b64 s41, s[100:101]
	v_mbcnt_lo_u32_b32 v12, s42, 0
	v_mbcnt_hi_u32_b32 v12, s43, v12
	v_mbcnt_lo_u32_b32 v13, s100, 0
	v_mbcnt_hi_u32_b32 v13, s101, v13
	s_add_i32 s98, s0, s1
	v_add_u32_e32 v12, s0, v12
	v_add_u32_e32 v13, s98, v13
	v_cndmask_b32_e64 v10, v10, v12, s[42:43]
	v_cndmask_b32_e64 v11, v11, v13, s[100:101]
	s_add_i32 s0, s98, s41
	v_cmp_eq_u32_e64 s[42:43], 7, v8
	v_cmp_eq_u32_e64 s[100:101], 7, v9
	s_bcnt1_i32_b64 s1, s[42:43]
	s_bcnt1_i32_b64 s41, s[100:101]
	v_mbcnt_lo_u32_b32 v12, s42, 0
	v_mbcnt_hi_u32_b32 v12, s43, v12
	v_mbcnt_lo_u32_b32 v13, s100, 0
	v_mbcnt_hi_u32_b32 v13, s101, v13
	s_add_i32 s98, s0, s1
	v_add_u32_e32 v12, s0, v12
	v_add_u32_e32 v13, s98, v13
	v_cndmask_b32_e64 v10, v10, v12, s[42:43]
	v_cndmask_b32_e64 v11, v11, v13, s[100:101]
	s_add_i32 s0, s98, s41
	s_and_b32 s1, s19, 1
	s_mul_i32 s1, s1, 0x7f
	v_xor_b32_e32 v10, s1, v10
	v_xor_b32_e32 v11, s1, v11
	v_lshl_add_u32 v10, v10, 2, v199
	v_lshl_add_u32 v11, v11, 2, v199
	ds_write_b32 v10, v4
	ds_write_b32 v11, v5
	ds_write_b32 v10, v6 offset:512
	ds_write_b32 v11, v7 offset:512
	v_add_u32_e32 v0, s48, v0
	v_cmp_gt_i32_e32 vcc, s52, v0
	v_mov_b32_e32 v2, s49
	v_mov_b32_e32 v3, s50
	v_cndmask_b32_e32 v2, v2, v3, vcc
	v_add_u32_e32 v152, v0, v2
	v_ashrrev_i32_e32 v153, 31, v152
	v_lshlrev_b64 v[2:3], 11, v[152:153]
	v_lshl_add_u64 v[2:3], v[138:139], 0, v[2:3]
	global_load_dwordx2 v[4:5], v[2:3], off
	global_load_dwordx2 v[6:7], v[2:3], off offset:512
	global_load_dwordx2 v[10:11], v[2:3], off offset:1024
	global_load_dwordx2 v[12:13], v[2:3], off offset:1536
	s_lshl_b32 s0, s19, 10
	v_add3_u32 v9, v131, s0, v136
	ds_read2st64_b32 v[14:15], v220 offset0:12 offset1:13
	ds_read2st64_b32 v[16:17], v220 offset0:14 offset1:15
	v_mov_b32_e32 v184, 0
	s_mov_b32 s1, 0
	v_mov_b32_e32 v185, v184
	v_mov_b32_e32 v186, v184
	v_mov_b32_e32 v187, v184
	v_mov_b32_e32 v182, v184
	v_mov_b32_e32 v183, v184
	v_mov_b32_e32 v180, v184
	v_mov_b32_e32 v181, v184
	v_mov_b32_e32 v178, v184
	v_mov_b32_e32 v179, v184
	v_mov_b32_e32 v176, v184
	v_mov_b32_e32 v177, v184
	v_mov_b32_e32 v174, v184
	v_mov_b32_e32 v175, v184
	v_mov_b32_e32 v172, v184
	v_mov_b32_e32 v173, v184
	s_waitcnt lgkmcnt(0)
	v_mov_b32_e32 v0, v14
	v_lshlrev_b64 v[18:19], 2, v[0:1]
	v_lshl_add_u64 v[20:21], s[34:35], 0, v[18:19]
	v_lshl_add_u64 v[18:19], s[90:91], 0, v[18:19]
	global_load_dword v8, v[20:21], off
	global_load_dword v22, v[18:19], off
	v_mov_b32_e32 v0, v15
	v_lshlrev_b64 v[18:19], 2, v[0:1]
	v_lshl_add_u64 v[20:21], s[34:35], 0, v[18:19]
	v_lshl_add_u64 v[18:19], s[90:91], 0, v[18:19]
	global_load_dword v23, v[20:21], off
	global_load_dword v24, v[18:19], off
	s_waitcnt vmcnt(0)
	v_lshlrev_b32_e32 v154, 16, v4
	v_and_b32_e32 v155, 0xffff0000, v4
	v_lshlrev_b32_e32 v156, 16, v5
	v_and_b32_e32 v157, 0xffff0000, v5
	v_lshlrev_b32_e32 v158, 16, v6
	v_and_b32_e32 v159, 0xffff0000, v6
	v_lshlrev_b32_e32 v162, 16, v7
	v_and_b32_e32 v163, 0xffff0000, v7
	v_lshlrev_b32_e32 v164, 16, v10
	v_and_b32_e32 v165, 0xffff0000, v10
	v_lshlrev_b32_e32 v166, 16, v11
	v_and_b32_e32 v167, 0xffff0000, v11
	v_lshlrev_b32_e32 v168, 16, v12
	v_and_b32_e32 v169, 0xffff0000, v12
	v_lshlrev_b32_e32 v170, 16, v13
	v_and_b32_e32 v171, 0xffff0000, v13
	v_mul_f32_e32 v6, v16, v22
	v_mul_f32_e32 v0, v17, v24
	ds_write2st64_b32 v9, v8, v23 offset1:1
	ds_write2st64_b32 v9, v6, v0 offset0:2 offset1:3
	v_readlane_b32 s98, v254, 28
	s_nop 0
	s_bitcmp1_b32 s98, 0
	s_cbranch_scc1 .Lprio_base_one
	s_setprio 0
	s_branch .Lprio_base_done
.Lprio_base_one:
	s_setprio 1
.Lprio_base_done:
.LBB0_870:
	v_add_u32_e32 v0, s1, v199
	ds_read_b128 v[2:5], v0
	ds_read_b128 v[6:9], v0 offset:16
	ds_read_b128 v[14:17], v0 offset:32
	ds_read_b128 v[26:29], v0 offset:48
	s_waitcnt lgkmcnt(3)
	v_readfirstlane_b32 s20, v2
	s_lshl_b64 s[42:43], s[20:21], 11
	v_lshl_add_u64 v[22:23], v[140:141], 0, s[42:43]
	global_load_dwordx4 v[126:129], v[22:23], off
	v_readfirstlane_b32 s20, v3
	s_lshl_b64 s[42:43], s[20:21], 11
	v_lshl_add_u64 v[24:25], v[140:141], 0, s[42:43]
	global_load_dwordx4 v[122:125], v[24:25], off
	v_readfirstlane_b32 s20, v4
	s_lshl_b64 s[42:43], s[20:21], 11
	v_lshl_add_u64 v[20:21], v[140:141], 0, s[42:43]
	global_load_dwordx4 v[118:121], v[20:21], off
	v_readfirstlane_b32 s20, v5
	s_lshl_b64 s[42:43], s[20:21], 11
	s_waitcnt lgkmcnt(2)
	v_readfirstlane_b32 s20, v6
	v_lshl_add_u64 v[18:19], v[140:141], 0, s[42:43]
	s_lshl_b64 s[42:43], s[20:21], 11
	v_readfirstlane_b32 s20, v7
	v_lshl_add_u64 v[10:11], v[140:141], 0, s[42:43]
	s_lshl_b64 s[42:43], s[20:21], 11
	v_readfirstlane_b32 s20, v8
	v_lshl_add_u64 v[2:3], v[140:141], 0, s[42:43]
	s_lshl_b64 s[42:43], s[20:21], 11
	v_readfirstlane_b32 s20, v9
	v_lshl_add_u64 v[4:5], v[140:141], 0, s[42:43]
	s_lshl_b64 s[42:43], s[20:21], 11
	s_waitcnt lgkmcnt(1)
	v_readfirstlane_b32 s20, v14
	v_lshl_add_u64 v[6:7], v[140:141], 0, s[42:43]
	s_lshl_b64 s[42:43], s[20:21], 11
	v_readfirstlane_b32 s20, v15
	global_load_dwordx4 v[114:117], v[18:19], off
	v_lshl_add_u64 v[8:9], v[140:141], 0, s[42:43]
	s_lshl_b64 s[42:43], s[20:21], 11
	v_readfirstlane_b32 s20, v16
	v_lshl_add_u64 v[12:13], v[140:141], 0, s[42:43]
	s_lshl_b64 s[42:43], s[20:21], 11
	v_readfirstlane_b32 s20, v17
	v_lshl_add_u64 v[14:15], v[140:141], 0, s[42:43]
	s_lshl_b64 s[42:43], s[20:21], 11
	s_waitcnt lgkmcnt(0)
	v_readfirstlane_b32 s20, v26
	v_lshl_add_u64 v[16:17], v[140:141], 0, s[42:43]
	s_lshl_b64 s[42:43], s[20:21], 11
	v_readfirstlane_b32 s20, v27
	v_lshl_add_u64 v[188:189], v[140:141], 0, s[42:43]
	s_lshl_b64 s[42:43], s[20:21], 11
	v_readfirstlane_b32 s20, v28
	v_lshl_add_u64 v[190:191], v[140:141], 0, s[42:43]
	s_lshl_b64 s[42:43], s[20:21], 11
	v_readfirstlane_b32 s20, v29
	v_lshl_add_u64 v[192:193], v[140:141], 0, s[42:43]
	s_lshl_b64 s[42:43], s[20:21], 11
	v_lshl_add_u64 v[194:195], v[140:141], 0, s[42:43]
	global_load_dwordx4 v[110:113], v[10:11], off
	global_load_dwordx4 v[90:93], v[12:13], off
	global_load_dwordx4 v[106:109], v[2:3], off
	global_load_dwordx4 v[102:105], v[4:5], off
	global_load_dwordx4 v[98:101], v[6:7], off
	global_load_dwordx4 v[94:97], v[8:9], off
	global_load_dwordx4 v[86:89], v[14:15], off
	global_load_dwordx4 v[82:85], v[16:17], off
	global_load_dwordx4 v[78:81], v[188:189], off
	global_load_dwordx4 v[74:77], v[190:191], off
	global_load_dwordx4 v[70:73], v[192:193], off
	global_load_dwordx4 v[66:69], v[194:195], off
	global_load_dwordx4 v[62:65], v[22:23], off offset:1024
	global_load_dwordx4 v[58:61], v[24:25], off offset:1024
	global_load_dwordx4 v[54:57], v[20:21], off offset:1024
	global_load_dwordx4 v[50:53], v[18:19], off offset:1024
	global_load_dwordx4 v[46:49], v[10:11], off offset:1024
	global_load_dwordx4 v[42:45], v[2:3], off offset:1024
	global_load_dwordx4 v[38:41], v[4:5], off offset:1024
	global_load_dwordx4 v[34:37], v[6:7], off offset:1024
	global_load_dwordx4 v[30:33], v[8:9], off offset:1024
	global_load_dwordx4 v[26:29], v[12:13], off offset:1024
	global_load_dwordx4 v[22:25], v[14:15], off offset:1024
	global_load_dwordx4 v[18:21], v[16:17], off offset:1024
	s_nop 0
	global_load_dwordx4 v[14:17], v[188:189], off offset:1024
	global_load_dwordx4 v[10:13], v[190:191], off offset:1024
	global_load_dwordx4 v[6:9], v[192:193], off offset:1024
	global_load_dwordx4 v[2:5], v[194:195], off offset:1024
	s_waitcnt vmcnt(31)
	v_cvt_pk_f32_fp8_e32 v[188:189], v126
	v_cvt_pk_f32_fp8_sdwa v[190:191], v126 src0_sel:WORD_1
	v_pk_fma_f32 v[188:189], v[188:189], v[154:155], 0 op_sel_hi:[1,1,0]
	s_nop 0
	v_pk_fma_f32 v[188:189], v[190:191], v[156:157], v[188:189]
	v_cvt_pk_f32_fp8_e32 v[190:191], v127
	v_cvt_pk_f32_fp8_sdwa v[126:127], v127 src0_sel:WORD_1
	v_pk_fma_f32 v[188:189], v[190:191], v[158:159], v[188:189]
	s_nop 0
	v_pk_fma_f32 v[126:127], v[126:127], v[162:163], v[188:189]
	v_cvt_pk_f32_fp8_e32 v[188:189], v128
	v_pk_fma_f32 v[126:127], v[188:189], v[164:165], v[126:127]
	v_cvt_pk_f32_fp8_sdwa v[188:189], v128 src0_sel:WORD_1
	v_pk_fma_f32 v[126:127], v[188:189], v[166:167], v[126:127]
	v_cvt_pk_f32_fp8_e32 v[188:189], v129
	v_cvt_pk_f32_fp8_sdwa v[128:129], v129 src0_sel:WORD_1
	v_pk_fma_f32 v[126:127], v[188:189], v[168:169], v[126:127]
	s_nop 0
	v_pk_fma_f32 v[126:127], v[128:129], v[170:171], v[126:127]
	s_waitcnt vmcnt(30)
	v_cvt_pk_f32_fp8_sdwa v[128:129], v122 src0_sel:WORD_1
	v_add_f32_e32 v0, v126, v127
	v_cvt_pk_f32_fp8_e32 v[126:127], v122
	v_pk_fma_f32 v[126:127], v[126:127], v[154:155], 0 op_sel_hi:[1,1,0]
	s_nop 0
	v_pk_fma_f32 v[126:127], v[128:129], v[156:157], v[126:127]
	v_cvt_pk_f32_fp8_e32 v[128:129], v123
	v_cvt_pk_f32_fp8_sdwa v[122:123], v123 src0_sel:WORD_1
	v_pk_fma_f32 v[126:127], v[128:129], v[158:159], v[126:127]
	s_nop 0
	v_pk_fma_f32 v[122:123], v[122:123], v[162:163], v[126:127]
	v_cvt_pk_f32_fp8_e32 v[126:127], v124
	v_pk_fma_f32 v[122:123], v[126:127], v[164:165], v[122:123]
	v_cvt_pk_f32_fp8_sdwa v[126:127], v124 src0_sel:WORD_1
	v_pk_fma_f32 v[122:123], v[126:127], v[166:167], v[122:123]
	v_cvt_pk_f32_fp8_e32 v[126:127], v125
	v_cvt_pk_f32_fp8_sdwa v[124:125], v125 src0_sel:WORD_1
	v_pk_fma_f32 v[122:123], v[126:127], v[168:169], v[122:123]
	s_nop 0
	v_pk_fma_f32 v[122:123], v[124:125], v[170:171], v[122:123]
	s_waitcnt vmcnt(29)
	v_cvt_pk_f32_fp8_sdwa v[124:125], v118 src0_sel:WORD_1
	v_add_f32_e32 v126, v122, v123
	v_cvt_pk_f32_fp8_e32 v[122:123], v118
	v_pk_fma_f32 v[122:123], v[122:123], v[154:155], 0 op_sel_hi:[1,1,0]
	s_nop 0
	v_pk_fma_f32 v[122:123], v[124:125], v[156:157], v[122:123]
	v_cvt_pk_f32_fp8_e32 v[124:125], v119
	v_cvt_pk_f32_fp8_sdwa v[118:119], v119 src0_sel:WORD_1
	v_pk_fma_f32 v[122:123], v[124:125], v[158:159], v[122:123]
	s_nop 0
	v_pk_fma_f32 v[118:119], v[118:119], v[162:163], v[122:123]
	v_cvt_pk_f32_fp8_e32 v[122:123], v120
	v_pk_fma_f32 v[118:119], v[122:123], v[164:165], v[118:119]
	v_cvt_pk_f32_fp8_sdwa v[122:123], v120 src0_sel:WORD_1
	v_pk_fma_f32 v[118:119], v[122:123], v[166:167], v[118:119]
	v_cvt_pk_f32_fp8_e32 v[122:123], v121
	v_cvt_pk_f32_fp8_sdwa v[120:121], v121 src0_sel:WORD_1
	v_pk_fma_f32 v[118:119], v[122:123], v[168:169], v[118:119]
	s_nop 0
	v_pk_fma_f32 v[118:119], v[120:121], v[170:171], v[118:119]
	s_waitcnt vmcnt(28)
	v_cvt_pk_f32_fp8_sdwa v[120:121], v114 src0_sel:WORD_1
	v_add_f32_e32 v122, v118, v119
	v_cvt_pk_f32_fp8_e32 v[118:119], v114
	v_pk_fma_f32 v[118:119], v[118:119], v[154:155], 0 op_sel_hi:[1,1,0]
	s_nop 0
	v_pk_fma_f32 v[118:119], v[120:121], v[156:157], v[118:119]
	v_cvt_pk_f32_fp8_e32 v[120:121], v115
	v_cvt_pk_f32_fp8_sdwa v[114:115], v115 src0_sel:WORD_1
	v_pk_fma_f32 v[118:119], v[120:121], v[158:159], v[118:119]
	s_nop 0
	v_pk_fma_f32 v[114:115], v[114:115], v[162:163], v[118:119]
	v_cvt_pk_f32_fp8_e32 v[118:119], v116
	v_pk_fma_f32 v[114:115], v[118:119], v[164:165], v[114:115]
	v_cvt_pk_f32_fp8_sdwa v[118:119], v116 src0_sel:WORD_1
	v_pk_fma_f32 v[114:115], v[118:119], v[166:167], v[114:115]
	v_cvt_pk_f32_fp8_e32 v[118:119], v117
	v_cvt_pk_f32_fp8_sdwa v[116:117], v117 src0_sel:WORD_1
	v_pk_fma_f32 v[114:115], v[118:119], v[168:169], v[114:115]
	s_nop 0
	v_pk_fma_f32 v[114:115], v[116:117], v[170:171], v[114:115]
	s_waitcnt vmcnt(27)
	v_cvt_pk_f32_fp8_sdwa v[116:117], v110 src0_sel:WORD_1
	v_add_f32_e32 v118, v114, v115
	v_cvt_pk_f32_fp8_e32 v[114:115], v110
	v_pk_fma_f32 v[114:115], v[114:115], v[154:155], 0 op_sel_hi:[1,1,0]
	s_nop 0
	v_pk_fma_f32 v[114:115], v[116:117], v[156:157], v[114:115]
	v_cvt_pk_f32_fp8_e32 v[116:117], v111
	v_cvt_pk_f32_fp8_sdwa v[110:111], v111 src0_sel:WORD_1
	v_pk_fma_f32 v[114:115], v[116:117], v[158:159], v[114:115]
	s_nop 0
	v_pk_fma_f32 v[110:111], v[110:111], v[162:163], v[114:115]
	v_cvt_pk_f32_fp8_e32 v[114:115], v112
	v_pk_fma_f32 v[110:111], v[114:115], v[164:165], v[110:111]
	v_cvt_pk_f32_fp8_sdwa v[114:115], v112 src0_sel:WORD_1
	v_pk_fma_f32 v[110:111], v[114:115], v[166:167], v[110:111]
	v_cvt_pk_f32_fp8_e32 v[114:115], v113
	v_cvt_pk_f32_fp8_sdwa v[112:113], v113 src0_sel:WORD_1
	v_pk_fma_f32 v[110:111], v[114:115], v[168:169], v[110:111]
	s_nop 0
	v_pk_fma_f32 v[110:111], v[112:113], v[170:171], v[110:111]
	s_waitcnt vmcnt(25)
	v_cvt_pk_f32_fp8_sdwa v[112:113], v106 src0_sel:WORD_1
	v_add_f32_e32 v114, v110, v111
	v_cvt_pk_f32_fp8_e32 v[110:111], v106
	v_pk_fma_f32 v[110:111], v[110:111], v[154:155], 0 op_sel_hi:[1,1,0]
	s_nop 0
	v_pk_fma_f32 v[110:111], v[112:113], v[156:157], v[110:111]
	v_cvt_pk_f32_fp8_e32 v[112:113], v107
	v_cvt_pk_f32_fp8_sdwa v[106:107], v107 src0_sel:WORD_1
	v_pk_fma_f32 v[110:111], v[112:113], v[158:159], v[110:111]
	s_nop 0
	v_pk_fma_f32 v[106:107], v[106:107], v[162:163], v[110:111]
	v_cvt_pk_f32_fp8_e32 v[110:111], v108
	v_pk_fma_f32 v[106:107], v[110:111], v[164:165], v[106:107]
	v_cvt_pk_f32_fp8_sdwa v[110:111], v108 src0_sel:WORD_1
	v_pk_fma_f32 v[106:107], v[110:111], v[166:167], v[106:107]
	v_cvt_pk_f32_fp8_e32 v[110:111], v109
	v_cvt_pk_f32_fp8_sdwa v[108:109], v109 src0_sel:WORD_1
	v_pk_fma_f32 v[106:107], v[110:111], v[168:169], v[106:107]
	s_nop 0
	v_pk_fma_f32 v[106:107], v[108:109], v[170:171], v[106:107]
	s_waitcnt vmcnt(24)
	v_cvt_pk_f32_fp8_sdwa v[108:109], v102 src0_sel:WORD_1
	v_add_f32_e32 v110, v106, v107
	v_cvt_pk_f32_fp8_e32 v[106:107], v102
	v_pk_fma_f32 v[106:107], v[106:107], v[154:155], 0 op_sel_hi:[1,1,0]
	s_nop 0
	v_pk_fma_f32 v[106:107], v[108:109], v[156:157], v[106:107]
	v_cvt_pk_f32_fp8_e32 v[108:109], v103
	v_cvt_pk_f32_fp8_sdwa v[102:103], v103 src0_sel:WORD_1
	v_pk_fma_f32 v[106:107], v[108:109], v[158:159], v[106:107]
	s_nop 0
	v_pk_fma_f32 v[102:103], v[102:103], v[162:163], v[106:107]
	v_cvt_pk_f32_fp8_e32 v[106:107], v104
	v_pk_fma_f32 v[102:103], v[106:107], v[164:165], v[102:103]
	v_cvt_pk_f32_fp8_sdwa v[106:107], v104 src0_sel:WORD_1
	v_pk_fma_f32 v[102:103], v[106:107], v[166:167], v[102:103]
	v_cvt_pk_f32_fp8_e32 v[106:107], v105
	v_cvt_pk_f32_fp8_sdwa v[104:105], v105 src0_sel:WORD_1
	v_pk_fma_f32 v[102:103], v[106:107], v[168:169], v[102:103]
	s_nop 0
	v_pk_fma_f32 v[102:103], v[104:105], v[170:171], v[102:103]
	s_waitcnt vmcnt(23)
	v_cvt_pk_f32_fp8_sdwa v[104:105], v98 src0_sel:WORD_1
	v_add_f32_e32 v106, v102, v103
	v_cvt_pk_f32_fp8_e32 v[102:103], v98
	v_pk_fma_f32 v[102:103], v[102:103], v[154:155], 0 op_sel_hi:[1,1,0]
	s_nop 0
	v_pk_fma_f32 v[102:103], v[104:105], v[156:157], v[102:103]
	v_cvt_pk_f32_fp8_e32 v[104:105], v99
	v_cvt_pk_f32_fp8_sdwa v[98:99], v99 src0_sel:WORD_1
	v_pk_fma_f32 v[102:103], v[104:105], v[158:159], v[102:103]
	s_nop 0
	v_pk_fma_f32 v[98:99], v[98:99], v[162:163], v[102:103]
	v_cvt_pk_f32_fp8_e32 v[102:103], v100
	v_pk_fma_f32 v[98:99], v[102:103], v[164:165], v[98:99]
	v_cvt_pk_f32_fp8_sdwa v[102:103], v100 src0_sel:WORD_1
	v_pk_fma_f32 v[98:99], v[102:103], v[166:167], v[98:99]
	v_cvt_pk_f32_fp8_e32 v[102:103], v101
	v_cvt_pk_f32_fp8_sdwa v[100:101], v101 src0_sel:WORD_1
	v_pk_fma_f32 v[98:99], v[102:103], v[168:169], v[98:99]
	s_nop 0
	v_pk_fma_f32 v[98:99], v[100:101], v[170:171], v[98:99]
	s_waitcnt vmcnt(22)
	v_cvt_pk_f32_fp8_sdwa v[100:101], v94 src0_sel:WORD_1
	v_add_f32_e32 v102, v98, v99
	v_cvt_pk_f32_fp8_e32 v[98:99], v94
	v_pk_fma_f32 v[98:99], v[98:99], v[154:155], 0 op_sel_hi:[1,1,0]
	s_nop 0
	v_pk_fma_f32 v[98:99], v[100:101], v[156:157], v[98:99]
	v_cvt_pk_f32_fp8_e32 v[100:101], v95
	v_cvt_pk_f32_fp8_sdwa v[94:95], v95 src0_sel:WORD_1
	v_pk_fma_f32 v[98:99], v[100:101], v[158:159], v[98:99]
	s_nop 0
	v_pk_fma_f32 v[94:95], v[94:95], v[162:163], v[98:99]
	v_cvt_pk_f32_fp8_e32 v[98:99], v96
	v_pk_fma_f32 v[94:95], v[98:99], v[164:165], v[94:95]
	v_cvt_pk_f32_fp8_sdwa v[98:99], v96 src0_sel:WORD_1
	v_pk_fma_f32 v[94:95], v[98:99], v[166:167], v[94:95]
	v_cvt_pk_f32_fp8_e32 v[98:99], v97
	v_cvt_pk_f32_fp8_sdwa v[96:97], v97 src0_sel:WORD_1
	v_pk_fma_f32 v[94:95], v[98:99], v[168:169], v[94:95]
	s_nop 0
	v_pk_fma_f32 v[94:95], v[96:97], v[170:171], v[94:95]
	v_cvt_pk_f32_fp8_sdwa v[96:97], v90 src0_sel:WORD_1
	v_add_f32_e32 v98, v94, v95
	v_cvt_pk_f32_fp8_e32 v[94:95], v90
	v_pk_fma_f32 v[94:95], v[94:95], v[154:155], 0 op_sel_hi:[1,1,0]
	s_nop 0
	v_pk_fma_f32 v[94:95], v[96:97], v[156:157], v[94:95]
	v_cvt_pk_f32_fp8_e32 v[96:97], v91
	v_cvt_pk_f32_fp8_sdwa v[90:91], v91 src0_sel:WORD_1
	v_pk_fma_f32 v[94:95], v[96:97], v[158:159], v[94:95]
	s_nop 0
	v_pk_fma_f32 v[90:91], v[90:91], v[162:163], v[94:95]
	v_cvt_pk_f32_fp8_e32 v[94:95], v92
	v_pk_fma_f32 v[90:91], v[94:95], v[164:165], v[90:91]
	v_cvt_pk_f32_fp8_sdwa v[94:95], v92 src0_sel:WORD_1
	v_pk_fma_f32 v[90:91], v[94:95], v[166:167], v[90:91]
	v_cvt_pk_f32_fp8_e32 v[94:95], v93
	v_cvt_pk_f32_fp8_sdwa v[92:93], v93 src0_sel:WORD_1
	v_pk_fma_f32 v[90:91], v[94:95], v[168:169], v[90:91]
	s_nop 0
	v_pk_fma_f32 v[90:91], v[92:93], v[170:171], v[90:91]
	s_waitcnt vmcnt(21)
	v_cvt_pk_f32_fp8_sdwa v[92:93], v86 src0_sel:WORD_1
	v_add_f32_e32 v94, v90, v91
	v_cvt_pk_f32_fp8_e32 v[90:91], v86
	v_pk_fma_f32 v[90:91], v[90:91], v[154:155], 0 op_sel_hi:[1,1,0]
	s_nop 0
	v_pk_fma_f32 v[90:91], v[92:93], v[156:157], v[90:91]
	v_cvt_pk_f32_fp8_e32 v[92:93], v87
	v_cvt_pk_f32_fp8_sdwa v[86:87], v87 src0_sel:WORD_1
	v_pk_fma_f32 v[90:91], v[92:93], v[158:159], v[90:91]
	s_nop 0
	v_pk_fma_f32 v[86:87], v[86:87], v[162:163], v[90:91]
	v_cvt_pk_f32_fp8_e32 v[90:91], v88
	v_pk_fma_f32 v[86:87], v[90:91], v[164:165], v[86:87]
	v_cvt_pk_f32_fp8_sdwa v[90:91], v88 src0_sel:WORD_1
	v_pk_fma_f32 v[86:87], v[90:91], v[166:167], v[86:87]
	v_cvt_pk_f32_fp8_e32 v[90:91], v89
	v_cvt_pk_f32_fp8_sdwa v[88:89], v89 src0_sel:WORD_1
	v_pk_fma_f32 v[86:87], v[90:91], v[168:169], v[86:87]
	s_nop 0
	v_pk_fma_f32 v[86:87], v[88:89], v[170:171], v[86:87]
	s_waitcnt vmcnt(20)
	v_cvt_pk_f32_fp8_sdwa v[88:89], v82 src0_sel:WORD_1
	v_add_f32_e32 v90, v86, v87
	v_cvt_pk_f32_fp8_e32 v[86:87], v82
	v_pk_fma_f32 v[86:87], v[86:87], v[154:155], 0 op_sel_hi:[1,1,0]
	s_nop 0
	v_pk_fma_f32 v[86:87], v[88:89], v[156:157], v[86:87]
	v_cvt_pk_f32_fp8_e32 v[88:89], v83
	v_cvt_pk_f32_fp8_sdwa v[82:83], v83 src0_sel:WORD_1
	v_pk_fma_f32 v[86:87], v[88:89], v[158:159], v[86:87]
	s_nop 0
	v_pk_fma_f32 v[82:83], v[82:83], v[162:163], v[86:87]
	v_cvt_pk_f32_fp8_e32 v[86:87], v84
	v_pk_fma_f32 v[82:83], v[86:87], v[164:165], v[82:83]
	v_cvt_pk_f32_fp8_sdwa v[86:87], v84 src0_sel:WORD_1
	v_pk_fma_f32 v[82:83], v[86:87], v[166:167], v[82:83]
	v_cvt_pk_f32_fp8_e32 v[86:87], v85
	v_cvt_pk_f32_fp8_sdwa v[84:85], v85 src0_sel:WORD_1
	v_pk_fma_f32 v[82:83], v[86:87], v[168:169], v[82:83]
	s_nop 0
	v_pk_fma_f32 v[82:83], v[84:85], v[170:171], v[82:83]
	s_waitcnt vmcnt(19)
	v_cvt_pk_f32_fp8_sdwa v[84:85], v78 src0_sel:WORD_1
	v_add_f32_e32 v86, v82, v83
	v_cvt_pk_f32_fp8_e32 v[82:83], v78
	v_pk_fma_f32 v[82:83], v[82:83], v[154:155], 0 op_sel_hi:[1,1,0]
	s_nop 0
	v_pk_fma_f32 v[82:83], v[84:85], v[156:157], v[82:83]
	v_cvt_pk_f32_fp8_e32 v[84:85], v79
	v_cvt_pk_f32_fp8_sdwa v[78:79], v79 src0_sel:WORD_1
	v_pk_fma_f32 v[82:83], v[84:85], v[158:159], v[82:83]
	s_nop 0
	v_pk_fma_f32 v[78:79], v[78:79], v[162:163], v[82:83]
	v_cvt_pk_f32_fp8_e32 v[82:83], v80
	v_pk_fma_f32 v[78:79], v[82:83], v[164:165], v[78:79]
	v_cvt_pk_f32_fp8_sdwa v[82:83], v80 src0_sel:WORD_1
	v_pk_fma_f32 v[78:79], v[82:83], v[166:167], v[78:79]
	v_cvt_pk_f32_fp8_e32 v[82:83], v81
	v_cvt_pk_f32_fp8_sdwa v[80:81], v81 src0_sel:WORD_1
	v_pk_fma_f32 v[78:79], v[82:83], v[168:169], v[78:79]
	s_nop 0
	v_pk_fma_f32 v[78:79], v[80:81], v[170:171], v[78:79]
	s_waitcnt vmcnt(18)
	v_cvt_pk_f32_fp8_sdwa v[80:81], v74 src0_sel:WORD_1
	v_add_f32_e32 v82, v78, v79
	v_cvt_pk_f32_fp8_e32 v[78:79], v74
	v_pk_fma_f32 v[78:79], v[78:79], v[154:155], 0 op_sel_hi:[1,1,0]
	s_nop 0
	v_pk_fma_f32 v[78:79], v[80:81], v[156:157], v[78:79]
	v_cvt_pk_f32_fp8_e32 v[80:81], v75
	v_cvt_pk_f32_fp8_sdwa v[74:75], v75 src0_sel:WORD_1
	v_pk_fma_f32 v[78:79], v[80:81], v[158:159], v[78:79]
	s_nop 0
	v_pk_fma_f32 v[74:75], v[74:75], v[162:163], v[78:79]
	v_cvt_pk_f32_fp8_e32 v[78:79], v76
	v_pk_fma_f32 v[74:75], v[78:79], v[164:165], v[74:75]
	v_cvt_pk_f32_fp8_sdwa v[78:79], v76 src0_sel:WORD_1
	v_pk_fma_f32 v[74:75], v[78:79], v[166:167], v[74:75]
	v_cvt_pk_f32_fp8_e32 v[78:79], v77
	v_cvt_pk_f32_fp8_sdwa v[76:77], v77 src0_sel:WORD_1
	v_pk_fma_f32 v[74:75], v[78:79], v[168:169], v[74:75]
	s_nop 0
	v_pk_fma_f32 v[74:75], v[76:77], v[170:171], v[74:75]
	s_waitcnt vmcnt(17)
	v_cvt_pk_f32_fp8_sdwa v[76:77], v70 src0_sel:WORD_1
	v_add_f32_e32 v78, v74, v75
	v_cvt_pk_f32_fp8_e32 v[74:75], v70
	v_pk_fma_f32 v[74:75], v[74:75], v[154:155], 0 op_sel_hi:[1,1,0]
	s_nop 0
	v_pk_fma_f32 v[74:75], v[76:77], v[156:157], v[74:75]
	v_cvt_pk_f32_fp8_e32 v[76:77], v71
	v_cvt_pk_f32_fp8_sdwa v[70:71], v71 src0_sel:WORD_1
	v_pk_fma_f32 v[74:75], v[76:77], v[158:159], v[74:75]
	s_nop 0
	v_pk_fma_f32 v[70:71], v[70:71], v[162:163], v[74:75]
	v_cvt_pk_f32_fp8_e32 v[74:75], v72
	s_waitcnt vmcnt(15)
	v_cvt_pk_f32_fp8_e32 v[76:77], v65
	v_pk_fma_f32 v[70:71], v[74:75], v[164:165], v[70:71]
	v_cvt_pk_f32_fp8_sdwa v[74:75], v72 src0_sel:WORD_1
	v_pk_fma_f32 v[70:71], v[74:75], v[166:167], v[70:71]
	v_cvt_pk_f32_fp8_e32 v[74:75], v73
	v_cvt_pk_f32_fp8_sdwa v[72:73], v73 src0_sel:WORD_1
	v_pk_fma_f32 v[70:71], v[74:75], v[168:169], v[70:71]
	s_nop 0
	v_pk_fma_f32 v[70:71], v[72:73], v[170:171], v[70:71]
	v_cvt_pk_f32_fp8_sdwa v[72:73], v66 src0_sel:WORD_1
	v_add_f32_e32 v74, v70, v71
	v_cvt_pk_f32_fp8_e32 v[70:71], v66
	v_pk_fma_f32 v[70:71], v[70:71], v[154:155], 0 op_sel_hi:[1,1,0]
	s_nop 0
	v_pk_fma_f32 v[70:71], v[72:73], v[156:157], v[70:71]
	v_cvt_pk_f32_fp8_e32 v[72:73], v67
	v_cvt_pk_f32_fp8_sdwa v[66:67], v67 src0_sel:WORD_1
	v_pk_fma_f32 v[70:71], v[72:73], v[158:159], v[70:71]
	s_nop 0
	v_pk_fma_f32 v[66:67], v[66:67], v[162:163], v[70:71]
	v_cvt_pk_f32_fp8_e32 v[70:71], v68
	v_pk_fma_f32 v[66:67], v[70:71], v[164:165], v[66:67]
	v_cvt_pk_f32_fp8_sdwa v[70:71], v68 src0_sel:WORD_1
	v_pk_fma_f32 v[66:67], v[70:71], v[166:167], v[66:67]
	v_cvt_pk_f32_fp8_e32 v[70:71], v69
	v_cvt_pk_f32_fp8_sdwa v[68:69], v69 src0_sel:WORD_1
	v_pk_fma_f32 v[66:67], v[70:71], v[168:169], v[66:67]
	s_nop 0
	v_pk_fma_f32 v[66:67], v[68:69], v[170:171], v[66:67]
	v_add_f32_e32 v66, v66, v67
	v_cndmask_b32_e64 v127, v0, v98, s[6:7]
	v_cndmask_b32_e64 v0, v98, v0, s[6:7]
	v_cndmask_b32_e64 v128, v126, v94, s[6:7]
	v_cndmask_b32_e64 v126, v94, v126, s[6:7]
	v_cndmask_b32_e64 v129, v122, v90, s[6:7]
	v_cndmask_b32_e64 v122, v90, v122, s[6:7]
	v_cndmask_b32_e64 v123, v118, v86, s[6:7]
	v_cndmask_b32_e64 v118, v86, v118, s[6:7]
	v_cndmask_b32_e64 v124, v114, v82, s[6:7]
	v_cndmask_b32_e64 v114, v82, v114, s[6:7]
	v_cndmask_b32_e64 v125, v110, v78, s[6:7]
	v_cndmask_b32_e64 v110, v78, v110, s[6:7]
	v_cndmask_b32_e64 v119, v106, v74, s[6:7]
	v_cndmask_b32_e64 v106, v74, v106, s[6:7]
	v_cndmask_b32_e64 v120, v102, v66, s[6:7]
	v_cndmask_b32_e64 v102, v66, v102, s[6:7]
	v_add_f32_dpp v0, v127, v0 quad_perm:[1,0,3,2] row_mask:0xf bank_mask:0xf
	v_add_f32_dpp v126, v128, v126 quad_perm:[1,0,3,2] row_mask:0xf bank_mask:0xf
	v_add_f32_dpp v122, v129, v122 quad_perm:[1,0,3,2] row_mask:0xf bank_mask:0xf
	v_add_f32_dpp v118, v123, v118 quad_perm:[1,0,3,2] row_mask:0xf bank_mask:0xf
	v_add_f32_dpp v114, v124, v114 quad_perm:[1,0,3,2] row_mask:0xf bank_mask:0xf
	v_add_f32_dpp v110, v125, v110 quad_perm:[1,0,3,2] row_mask:0xf bank_mask:0xf
	v_add_f32_dpp v106, v119, v106 quad_perm:[1,0,3,2] row_mask:0xf bank_mask:0xf
	v_add_f32_dpp v102, v120, v102 quad_perm:[1,0,3,2] row_mask:0xf bank_mask:0xf
	v_cndmask_b32_e64 v127, v0, v114, s[8:9]
	v_cndmask_b32_e64 v0, v114, v0, s[8:9]
	v_cndmask_b32_e64 v128, v126, v110, s[8:9]
	v_cndmask_b32_e64 v126, v110, v126, s[8:9]
	v_cndmask_b32_e64 v129, v122, v106, s[8:9]
	v_cndmask_b32_e64 v122, v106, v122, s[8:9]
	v_cndmask_b32_e64 v123, v118, v102, s[8:9]
	v_cndmask_b32_e64 v118, v102, v118, s[8:9]
	v_add_f32_dpp v0, v127, v0 quad_perm:[2,3,0,1] row_mask:0xf bank_mask:0xf
	v_add_f32_dpp v126, v128, v126 quad_perm:[2,3,0,1] row_mask:0xf bank_mask:0xf
	v_add_f32_dpp v122, v129, v122 quad_perm:[2,3,0,1] row_mask:0xf bank_mask:0xf
	v_add_f32_dpp v118, v123, v118 quad_perm:[2,3,0,1] row_mask:0xf bank_mask:0xf
	v_cndmask_b32_e64 v127, v0, v122, s[10:11]
	v_cndmask_b32_e64 v0, v122, v0, s[10:11]
	v_cndmask_b32_e64 v128, v126, v118, s[10:11]
	v_cndmask_b32_e64 v126, v118, v126, s[10:11]
	v_mov_b32_dpp v129, v127 row_half_mirror row_mask:0xf bank_mask:0xf
	v_mov_b32_dpp v123, v128 row_half_mirror row_mask:0xf bank_mask:0xf
	s_nop 0
	v_add_f32_dpp v0, v129, v0 quad_perm:[3,2,1,0] row_mask:0xf bank_mask:0xf
	v_add_f32_dpp v126, v123, v126 quad_perm:[3,2,1,0] row_mask:0xf bank_mask:0xf
	v_cndmask_b32_e64 v127, v0, v126, s[12:13]
	v_cndmask_b32_e64 v0, v126, v0, s[12:13]
	s_nop 1
	v_add_f32_dpp v0, v127, v0 row_ror:8 row_mask:0xf bank_mask:0xf
	s_waitcnt vmcnt(14)
	v_cvt_pk_f32_fp8_e32 v[78:79], v58
	v_cvt_pk_f32_fp8_sdwa v[74:75], v64 src0_sel:WORD_1
	ds_bpermute_b32 v66, v214, v0
	s_waitcnt lgkmcnt(0)
	v_add_f32_e32 v0, v0, v66
	ds_bpermute_b32 v66, v215, v0
	s_waitcnt lgkmcnt(0)
	v_add_f32_e32 v0, v0, v66
	v_add_u32_e32 v66, s1, v151
	ds_read2st64_b32 v[66:67], v66 offset1:2
	s_waitcnt lgkmcnt(0)
	v_mul_f32_e32 v0, v66, v0
	v_mul_f32_e32 v66, 0x3d372713, v0
	v_mul_f32_e32 v66, v0, v66
	v_fma_f32 v66, v0, v66, v0
	v_mul_f32_e32 v66, 0xbfcc422a, v66
	v_mul_f32_e32 v66, 0x3fb8aa3b, v66
	v_exp_f32_e32 v66, v66
	s_nop 0
	v_add_f32_e32 v66, 1.0, v66
	v_div_scale_f32 v68, s[42:43], v66, v66, v0
	v_rcp_f32_e32 v69, v68
	s_nop 0
	v_fma_f32 v70, -v68, v69, 1.0
	v_fmac_f32_e32 v69, v70, v69
	v_div_scale_f32 v70, vcc, v0, v66, v0
	v_mul_f32_e32 v71, v70, v69
	v_fma_f32 v72, -v68, v71, v70
	v_fmac_f32_e32 v71, v72, v69
	v_fma_f32 v68, -v68, v71, v70
	v_div_fmas_f32 v68, v68, v69, v71
	v_div_fixup_f32 v0, v68, v66, v0
	v_mul_f32_e32 v0, v67, v0
	v_cvt_pk_f32_fp8_e32 v[66:67], v62
	v_cvt_pk_f32_fp8_sdwa v[68:69], v62 src0_sel:WORD_1
	v_cvt_pk_f32_fp8_e32 v[70:71], v63
	v_cvt_pk_f32_fp8_sdwa v[62:63], v63 src0_sel:WORD_1
	v_cvt_pk_f32_fp8_e32 v[72:73], v64
	v_cvt_pk_f32_fp8_sdwa v[64:65], v65 src0_sel:WORD_1
	v_readlane_b32 s0, v0, 0
	s_nop 1
	v_pk_fma_f32 v[66:67], v[66:67], s[0:1], v[184:185] op_sel_hi:[1,0,1]
	v_pk_fma_f32 v[68:69], v[68:69], s[0:1], v[186:187] op_sel_hi:[1,0,1]
	v_pk_fma_f32 v[70:71], v[70:71], s[0:1], v[182:183] op_sel_hi:[1,0,1]
	v_pk_fma_f32 v[62:63], v[62:63], s[0:1], v[180:181] op_sel_hi:[1,0,1]
	v_pk_fma_f32 v[72:73], v[72:73], s[0:1], v[178:179] op_sel_hi:[1,0,1]
	v_pk_fma_f32 v[74:75], v[74:75], s[0:1], v[176:177] op_sel_hi:[1,0,1]
	v_pk_fma_f32 v[76:77], v[76:77], s[0:1], v[174:175] op_sel_hi:[1,0,1]
	v_pk_fma_f32 v[64:65], v[64:65], s[0:1], v[172:173] op_sel_hi:[1,0,1]
	v_readlane_b32 s0, v0, 8
	s_nop 1
	v_pk_fma_f32 v[66:67], v[78:79], s[0:1], v[66:67] op_sel_hi:[1,0,1]
	v_cvt_pk_f32_fp8_sdwa v[78:79], v58 src0_sel:WORD_1
	v_pk_fma_f32 v[68:69], v[78:79], s[0:1], v[68:69] op_sel_hi:[1,0,1]
	v_cvt_pk_f32_fp8_e32 v[78:79], v59
	v_cvt_pk_f32_fp8_sdwa v[58:59], v59 src0_sel:WORD_1
	v_pk_fma_f32 v[70:71], v[78:79], s[0:1], v[70:71] op_sel_hi:[1,0,1]
	v_pk_fma_f32 v[58:59], v[58:59], s[0:1], v[62:63] op_sel_hi:[1,0,1]
	v_cvt_pk_f32_fp8_e32 v[62:63], v60
	v_pk_fma_f32 v[62:63], v[62:63], s[0:1], v[72:73] op_sel_hi:[1,0,1]
	v_cvt_pk_f32_fp8_sdwa v[72:73], v60 src0_sel:WORD_1
	v_pk_fma_f32 v[72:73], v[72:73], s[0:1], v[74:75] op_sel_hi:[1,0,1]
	v_cvt_pk_f32_fp8_e32 v[74:75], v61
	v_cvt_pk_f32_fp8_sdwa v[60:61], v61 src0_sel:WORD_1
	v_pk_fma_f32 v[74:75], v[74:75], s[0:1], v[76:77] op_sel_hi:[1,0,1]
	v_pk_fma_f32 v[60:61], v[60:61], s[0:1], v[64:65] op_sel_hi:[1,0,1]
	s_waitcnt vmcnt(13)
	v_cvt_pk_f32_fp8_e32 v[64:65], v54
	v_readlane_b32 s0, v0, 4
	s_nop 1
	v_pk_fma_f32 v[64:65], v[64:65], s[0:1], v[66:67] op_sel_hi:[1,0,1]
	v_cvt_pk_f32_fp8_sdwa v[66:67], v54 src0_sel:WORD_1
	v_pk_fma_f32 v[66:67], v[66:67], s[0:1], v[68:69] op_sel_hi:[1,0,1]
	v_cvt_pk_f32_fp8_e32 v[68:69], v55
	v_cvt_pk_f32_fp8_sdwa v[54:55], v55 src0_sel:WORD_1
	v_pk_fma_f32 v[68:69], v[68:69], s[0:1], v[70:71] op_sel_hi:[1,0,1]
	v_pk_fma_f32 v[54:55], v[54:55], s[0:1], v[58:59] op_sel_hi:[1,0,1]
	v_cvt_pk_f32_fp8_e32 v[58:59], v56
	v_cvt_pk_f32_fp8_e32 v[70:71], v57
	v_pk_fma_f32 v[58:59], v[58:59], s[0:1], v[62:63] op_sel_hi:[1,0,1]
	v_cvt_pk_f32_fp8_sdwa v[62:63], v56 src0_sel:WORD_1
	v_cvt_pk_f32_fp8_sdwa v[56:57], v57 src0_sel:WORD_1
	v_pk_fma_f32 v[70:71], v[70:71], s[0:1], v[74:75] op_sel_hi:[1,0,1]
	v_pk_fma_f32 v[62:63], v[62:63], s[0:1], v[72:73] op_sel_hi:[1,0,1]
	v_pk_fma_f32 v[56:57], v[56:57], s[0:1], v[60:61] op_sel_hi:[1,0,1]
	s_waitcnt vmcnt(12)
	v_cvt_pk_f32_fp8_e32 v[60:61], v50
	v_readlane_b32 s0, v0, 12
	s_nop 1
	v_pk_fma_f32 v[60:61], v[60:61], s[0:1], v[64:65] op_sel_hi:[1,0,1]
	v_cvt_pk_f32_fp8_sdwa v[64:65], v50 src0_sel:WORD_1
	v_pk_fma_f32 v[64:65], v[64:65], s[0:1], v[66:67] op_sel_hi:[1,0,1]
	v_cvt_pk_f32_fp8_e32 v[66:67], v51
	v_cvt_pk_f32_fp8_sdwa v[50:51], v51 src0_sel:WORD_1
	v_pk_fma_f32 v[66:67], v[66:67], s[0:1], v[68:69] op_sel_hi:[1,0,1]
	v_pk_fma_f32 v[50:51], v[50:51], s[0:1], v[54:55] op_sel_hi:[1,0,1]
	v_cvt_pk_f32_fp8_e32 v[54:55], v52
	v_pk_fma_f32 v[54:55], v[54:55], s[0:1], v[58:59] op_sel_hi:[1,0,1]
	v_cvt_pk_f32_fp8_sdwa v[58:59], v52 src0_sel:WORD_1
	v_pk_fma_f32 v[58:59], v[58:59], s[0:1], v[62:63] op_sel_hi:[1,0,1]
	v_cvt_pk_f32_fp8_e32 v[62:63], v53
	v_cvt_pk_f32_fp8_sdwa v[52:53], v53 src0_sel:WORD_1
	v_pk_fma_f32 v[62:63], v[62:63], s[0:1], v[70:71] op_sel_hi:[1,0,1]
	v_pk_fma_f32 v[52:53], v[52:53], s[0:1], v[56:57] op_sel_hi:[1,0,1]
	s_waitcnt vmcnt(11)
	v_cvt_pk_f32_fp8_e32 v[56:57], v46
	v_readlane_b32 s0, v0, 2
	s_nop 1
	v_pk_fma_f32 v[56:57], v[56:57], s[0:1], v[60:61] op_sel_hi:[1,0,1]
	v_cvt_pk_f32_fp8_sdwa v[60:61], v46 src0_sel:WORD_1
	v_pk_fma_f32 v[60:61], v[60:61], s[0:1], v[64:65] op_sel_hi:[1,0,1]
	v_cvt_pk_f32_fp8_e32 v[64:65], v47
	v_cvt_pk_f32_fp8_sdwa v[46:47], v47 src0_sel:WORD_1
	v_pk_fma_f32 v[64:65], v[64:65], s[0:1], v[66:67] op_sel_hi:[1,0,1]
	v_pk_fma_f32 v[46:47], v[46:47], s[0:1], v[50:51] op_sel_hi:[1,0,1]
	v_cvt_pk_f32_fp8_e32 v[50:51], v48
	v_pk_fma_f32 v[50:51], v[50:51], s[0:1], v[54:55] op_sel_hi:[1,0,1]
	v_cvt_pk_f32_fp8_sdwa v[54:55], v48 src0_sel:WORD_1
	v_pk_fma_f32 v[54:55], v[54:55], s[0:1], v[58:59] op_sel_hi:[1,0,1]
	v_cvt_pk_f32_fp8_e32 v[58:59], v49
	v_cvt_pk_f32_fp8_sdwa v[48:49], v49 src0_sel:WORD_1
	v_pk_fma_f32 v[58:59], v[58:59], s[0:1], v[62:63] op_sel_hi:[1,0,1]
	v_pk_fma_f32 v[48:49], v[48:49], s[0:1], v[52:53] op_sel_hi:[1,0,1]
	s_waitcnt vmcnt(10)
	v_cvt_pk_f32_fp8_e32 v[52:53], v42
	v_readlane_b32 s0, v0, 10
	s_nop 1
	v_pk_fma_f32 v[52:53], v[52:53], s[0:1], v[56:57] op_sel_hi:[1,0,1]
	v_cvt_pk_f32_fp8_sdwa v[56:57], v42 src0_sel:WORD_1
	v_pk_fma_f32 v[56:57], v[56:57], s[0:1], v[60:61] op_sel_hi:[1,0,1]
	v_cvt_pk_f32_fp8_e32 v[60:61], v43
	v_cvt_pk_f32_fp8_sdwa v[42:43], v43 src0_sel:WORD_1
	v_pk_fma_f32 v[60:61], v[60:61], s[0:1], v[64:65] op_sel_hi:[1,0,1]
	v_pk_fma_f32 v[42:43], v[42:43], s[0:1], v[46:47] op_sel_hi:[1,0,1]
	v_cvt_pk_f32_fp8_e32 v[46:47], v44
	v_pk_fma_f32 v[46:47], v[46:47], s[0:1], v[50:51] op_sel_hi:[1,0,1]
	v_cvt_pk_f32_fp8_sdwa v[50:51], v44 src0_sel:WORD_1
	v_pk_fma_f32 v[50:51], v[50:51], s[0:1], v[54:55] op_sel_hi:[1,0,1]
	v_cvt_pk_f32_fp8_e32 v[54:55], v45
	v_cvt_pk_f32_fp8_sdwa v[44:45], v45 src0_sel:WORD_1
	v_pk_fma_f32 v[54:55], v[54:55], s[0:1], v[58:59] op_sel_hi:[1,0,1]
	v_pk_fma_f32 v[44:45], v[44:45], s[0:1], v[48:49] op_sel_hi:[1,0,1]
	s_waitcnt vmcnt(9)
	v_cvt_pk_f32_fp8_e32 v[48:49], v38
	v_readlane_b32 s0, v0, 6
	s_nop 1
	v_pk_fma_f32 v[48:49], v[48:49], s[0:1], v[52:53] op_sel_hi:[1,0,1]
	v_cvt_pk_f32_fp8_sdwa v[52:53], v38 src0_sel:WORD_1
	v_pk_fma_f32 v[52:53], v[52:53], s[0:1], v[56:57] op_sel_hi:[1,0,1]
	v_cvt_pk_f32_fp8_e32 v[56:57], v39
	v_cvt_pk_f32_fp8_sdwa v[38:39], v39 src0_sel:WORD_1
	v_pk_fma_f32 v[56:57], v[56:57], s[0:1], v[60:61] op_sel_hi:[1,0,1]
	v_pk_fma_f32 v[38:39], v[38:39], s[0:1], v[42:43] op_sel_hi:[1,0,1]
	v_cvt_pk_f32_fp8_e32 v[42:43], v40
	v_pk_fma_f32 v[42:43], v[42:43], s[0:1], v[46:47] op_sel_hi:[1,0,1]
	v_cvt_pk_f32_fp8_sdwa v[46:47], v40 src0_sel:WORD_1
	v_pk_fma_f32 v[46:47], v[46:47], s[0:1], v[50:51] op_sel_hi:[1,0,1]
	v_cvt_pk_f32_fp8_e32 v[50:51], v41
	v_cvt_pk_f32_fp8_sdwa v[40:41], v41 src0_sel:WORD_1
	v_pk_fma_f32 v[50:51], v[50:51], s[0:1], v[54:55] op_sel_hi:[1,0,1]
	v_pk_fma_f32 v[40:41], v[40:41], s[0:1], v[44:45] op_sel_hi:[1,0,1]
	s_waitcnt vmcnt(8)
	v_cvt_pk_f32_fp8_e32 v[44:45], v34
	v_readlane_b32 s0, v0, 14
	s_nop 1
	v_pk_fma_f32 v[44:45], v[44:45], s[0:1], v[48:49] op_sel_hi:[1,0,1]
	v_cvt_pk_f32_fp8_sdwa v[48:49], v34 src0_sel:WORD_1
	v_pk_fma_f32 v[48:49], v[48:49], s[0:1], v[52:53] op_sel_hi:[1,0,1]
	v_cvt_pk_f32_fp8_e32 v[52:53], v35
	v_cvt_pk_f32_fp8_sdwa v[34:35], v35 src0_sel:WORD_1
	v_pk_fma_f32 v[52:53], v[52:53], s[0:1], v[56:57] op_sel_hi:[1,0,1]
	v_pk_fma_f32 v[34:35], v[34:35], s[0:1], v[38:39] op_sel_hi:[1,0,1]
	v_cvt_pk_f32_fp8_e32 v[38:39], v36
	v_pk_fma_f32 v[38:39], v[38:39], s[0:1], v[42:43] op_sel_hi:[1,0,1]
	v_cvt_pk_f32_fp8_sdwa v[42:43], v36 src0_sel:WORD_1
	v_pk_fma_f32 v[42:43], v[42:43], s[0:1], v[46:47] op_sel_hi:[1,0,1]
	v_cvt_pk_f32_fp8_e32 v[46:47], v37
	v_cvt_pk_f32_fp8_sdwa v[36:37], v37 src0_sel:WORD_1
	v_pk_fma_f32 v[46:47], v[46:47], s[0:1], v[50:51] op_sel_hi:[1,0,1]
	v_pk_fma_f32 v[36:37], v[36:37], s[0:1], v[40:41] op_sel_hi:[1,0,1]
	s_waitcnt vmcnt(7)
	v_cvt_pk_f32_fp8_e32 v[40:41], v30
	v_readlane_b32 s0, v0, 1
	s_nop 1
	v_pk_fma_f32 v[40:41], v[40:41], s[0:1], v[44:45] op_sel_hi:[1,0,1]
	v_cvt_pk_f32_fp8_sdwa v[44:45], v30 src0_sel:WORD_1
	v_pk_fma_f32 v[44:45], v[44:45], s[0:1], v[48:49] op_sel_hi:[1,0,1]
	v_cvt_pk_f32_fp8_e32 v[48:49], v31
	v_cvt_pk_f32_fp8_sdwa v[30:31], v31 src0_sel:WORD_1
	v_pk_fma_f32 v[48:49], v[48:49], s[0:1], v[52:53] op_sel_hi:[1,0,1]
	v_pk_fma_f32 v[30:31], v[30:31], s[0:1], v[34:35] op_sel_hi:[1,0,1]
	v_cvt_pk_f32_fp8_e32 v[34:35], v32
	v_pk_fma_f32 v[34:35], v[34:35], s[0:1], v[38:39] op_sel_hi:[1,0,1]
	v_cvt_pk_f32_fp8_sdwa v[38:39], v32 src0_sel:WORD_1
	v_pk_fma_f32 v[38:39], v[38:39], s[0:1], v[42:43] op_sel_hi:[1,0,1]
	v_cvt_pk_f32_fp8_e32 v[42:43], v33
	v_cvt_pk_f32_fp8_sdwa v[32:33], v33 src0_sel:WORD_1
	v_pk_fma_f32 v[42:43], v[42:43], s[0:1], v[46:47] op_sel_hi:[1,0,1]
	v_pk_fma_f32 v[32:33], v[32:33], s[0:1], v[36:37] op_sel_hi:[1,0,1]
	s_waitcnt vmcnt(6)
	v_cvt_pk_f32_fp8_e32 v[36:37], v26
	v_readlane_b32 s0, v0, 9
	s_nop 1
	v_pk_fma_f32 v[36:37], v[36:37], s[0:1], v[40:41] op_sel_hi:[1,0,1]
	v_cvt_pk_f32_fp8_sdwa v[40:41], v26 src0_sel:WORD_1
	v_pk_fma_f32 v[40:41], v[40:41], s[0:1], v[44:45] op_sel_hi:[1,0,1]
	v_cvt_pk_f32_fp8_e32 v[44:45], v27
	v_cvt_pk_f32_fp8_sdwa v[26:27], v27 src0_sel:WORD_1
	v_pk_fma_f32 v[44:45], v[44:45], s[0:1], v[48:49] op_sel_hi:[1,0,1]
	v_pk_fma_f32 v[26:27], v[26:27], s[0:1], v[30:31] op_sel_hi:[1,0,1]
	v_cvt_pk_f32_fp8_e32 v[30:31], v28
	v_pk_fma_f32 v[30:31], v[30:31], s[0:1], v[34:35] op_sel_hi:[1,0,1]
	v_cvt_pk_f32_fp8_sdwa v[34:35], v28 src0_sel:WORD_1
	v_pk_fma_f32 v[34:35], v[34:35], s[0:1], v[38:39] op_sel_hi:[1,0,1]
	v_cvt_pk_f32_fp8_e32 v[38:39], v29
	v_cvt_pk_f32_fp8_sdwa v[28:29], v29 src0_sel:WORD_1
	v_pk_fma_f32 v[38:39], v[38:39], s[0:1], v[42:43] op_sel_hi:[1,0,1]
	v_pk_fma_f32 v[28:29], v[28:29], s[0:1], v[32:33] op_sel_hi:[1,0,1]
	s_waitcnt vmcnt(5)
	v_cvt_pk_f32_fp8_e32 v[32:33], v22
	v_readlane_b32 s0, v0, 5
	s_nop 1
	v_pk_fma_f32 v[32:33], v[32:33], s[0:1], v[36:37] op_sel_hi:[1,0,1]
	v_cvt_pk_f32_fp8_sdwa v[36:37], v22 src0_sel:WORD_1
	v_pk_fma_f32 v[36:37], v[36:37], s[0:1], v[40:41] op_sel_hi:[1,0,1]
	v_cvt_pk_f32_fp8_e32 v[40:41], v23
	v_cvt_pk_f32_fp8_sdwa v[22:23], v23 src0_sel:WORD_1
	v_pk_fma_f32 v[40:41], v[40:41], s[0:1], v[44:45] op_sel_hi:[1,0,1]
	v_pk_fma_f32 v[22:23], v[22:23], s[0:1], v[26:27] op_sel_hi:[1,0,1]
	v_cvt_pk_f32_fp8_e32 v[26:27], v24
	v_pk_fma_f32 v[26:27], v[26:27], s[0:1], v[30:31] op_sel_hi:[1,0,1]
	v_cvt_pk_f32_fp8_sdwa v[30:31], v24 src0_sel:WORD_1
	v_pk_fma_f32 v[30:31], v[30:31], s[0:1], v[34:35] op_sel_hi:[1,0,1]
	v_cvt_pk_f32_fp8_e32 v[34:35], v25
	v_cvt_pk_f32_fp8_sdwa v[24:25], v25 src0_sel:WORD_1
	v_pk_fma_f32 v[34:35], v[34:35], s[0:1], v[38:39] op_sel_hi:[1,0,1]
	v_pk_fma_f32 v[24:25], v[24:25], s[0:1], v[28:29] op_sel_hi:[1,0,1]
	s_waitcnt vmcnt(4)
	v_cvt_pk_f32_fp8_e32 v[28:29], v18
	v_readlane_b32 s0, v0, 13
	s_nop 1
	v_pk_fma_f32 v[28:29], v[28:29], s[0:1], v[32:33] op_sel_hi:[1,0,1]
	v_cvt_pk_f32_fp8_sdwa v[32:33], v18 src0_sel:WORD_1
	v_pk_fma_f32 v[32:33], v[32:33], s[0:1], v[36:37] op_sel_hi:[1,0,1]
	v_cvt_pk_f32_fp8_e32 v[36:37], v19
	v_cvt_pk_f32_fp8_sdwa v[18:19], v19 src0_sel:WORD_1
	v_pk_fma_f32 v[36:37], v[36:37], s[0:1], v[40:41] op_sel_hi:[1,0,1]
	v_pk_fma_f32 v[18:19], v[18:19], s[0:1], v[22:23] op_sel_hi:[1,0,1]
	v_cvt_pk_f32_fp8_e32 v[22:23], v20
	v_pk_fma_f32 v[22:23], v[22:23], s[0:1], v[26:27] op_sel_hi:[1,0,1]
	v_cvt_pk_f32_fp8_sdwa v[26:27], v20 src0_sel:WORD_1
	v_pk_fma_f32 v[26:27], v[26:27], s[0:1], v[30:31] op_sel_hi:[1,0,1]
	v_cvt_pk_f32_fp8_e32 v[30:31], v21
	v_cvt_pk_f32_fp8_sdwa v[20:21], v21 src0_sel:WORD_1
	v_pk_fma_f32 v[30:31], v[30:31], s[0:1], v[34:35] op_sel_hi:[1,0,1]
	v_pk_fma_f32 v[20:21], v[20:21], s[0:1], v[24:25] op_sel_hi:[1,0,1]
	s_waitcnt vmcnt(3)
	v_cvt_pk_f32_fp8_e32 v[24:25], v14
	v_readlane_b32 s0, v0, 3
	s_nop 1
	v_pk_fma_f32 v[24:25], v[24:25], s[0:1], v[28:29] op_sel_hi:[1,0,1]
	v_cvt_pk_f32_fp8_sdwa v[28:29], v14 src0_sel:WORD_1
	v_pk_fma_f32 v[28:29], v[28:29], s[0:1], v[32:33] op_sel_hi:[1,0,1]
	v_cvt_pk_f32_fp8_e32 v[32:33], v15
	v_cvt_pk_f32_fp8_sdwa v[14:15], v15 src0_sel:WORD_1
	v_pk_fma_f32 v[32:33], v[32:33], s[0:1], v[36:37] op_sel_hi:[1,0,1]
	v_pk_fma_f32 v[14:15], v[14:15], s[0:1], v[18:19] op_sel_hi:[1,0,1]
	v_cvt_pk_f32_fp8_e32 v[18:19], v16
	v_pk_fma_f32 v[18:19], v[18:19], s[0:1], v[22:23] op_sel_hi:[1,0,1]
	v_cvt_pk_f32_fp8_sdwa v[22:23], v16 src0_sel:WORD_1
	v_pk_fma_f32 v[22:23], v[22:23], s[0:1], v[26:27] op_sel_hi:[1,0,1]
	v_cvt_pk_f32_fp8_e32 v[26:27], v17
	v_cvt_pk_f32_fp8_sdwa v[16:17], v17 src0_sel:WORD_1
	v_pk_fma_f32 v[26:27], v[26:27], s[0:1], v[30:31] op_sel_hi:[1,0,1]
	v_pk_fma_f32 v[16:17], v[16:17], s[0:1], v[20:21] op_sel_hi:[1,0,1]
	s_waitcnt vmcnt(2)
	v_cvt_pk_f32_fp8_e32 v[20:21], v10
	v_readlane_b32 s0, v0, 11
	s_nop 1
	v_pk_fma_f32 v[20:21], v[20:21], s[0:1], v[24:25] op_sel_hi:[1,0,1]
	v_cvt_pk_f32_fp8_sdwa v[24:25], v10 src0_sel:WORD_1
	v_pk_fma_f32 v[24:25], v[24:25], s[0:1], v[28:29] op_sel_hi:[1,0,1]
	v_cvt_pk_f32_fp8_e32 v[28:29], v11
	v_cvt_pk_f32_fp8_sdwa v[10:11], v11 src0_sel:WORD_1
	v_pk_fma_f32 v[28:29], v[28:29], s[0:1], v[32:33] op_sel_hi:[1,0,1]
	v_pk_fma_f32 v[10:11], v[10:11], s[0:1], v[14:15] op_sel_hi:[1,0,1]
	v_cvt_pk_f32_fp8_e32 v[14:15], v12
	v_pk_fma_f32 v[14:15], v[14:15], s[0:1], v[18:19] op_sel_hi:[1,0,1]
	v_cvt_pk_f32_fp8_sdwa v[18:19], v12 src0_sel:WORD_1
	v_pk_fma_f32 v[18:19], v[18:19], s[0:1], v[22:23] op_sel_hi:[1,0,1]
	v_cvt_pk_f32_fp8_e32 v[22:23], v13
	v_cvt_pk_f32_fp8_sdwa v[12:13], v13 src0_sel:WORD_1
	v_pk_fma_f32 v[22:23], v[22:23], s[0:1], v[26:27] op_sel_hi:[1,0,1]
	v_pk_fma_f32 v[12:13], v[12:13], s[0:1], v[16:17] op_sel_hi:[1,0,1]
	s_waitcnt vmcnt(1)
	v_cvt_pk_f32_fp8_e32 v[16:17], v6
	v_readlane_b32 s0, v0, 7
	s_nop 1
	v_pk_fma_f32 v[16:17], v[16:17], s[0:1], v[20:21] op_sel_hi:[1,0,1]
	v_cvt_pk_f32_fp8_sdwa v[20:21], v6 src0_sel:WORD_1
	v_pk_fma_f32 v[20:21], v[20:21], s[0:1], v[24:25] op_sel_hi:[1,0,1]
	v_cvt_pk_f32_fp8_e32 v[24:25], v7
	v_cvt_pk_f32_fp8_sdwa v[6:7], v7 src0_sel:WORD_1
	v_pk_fma_f32 v[24:25], v[24:25], s[0:1], v[28:29] op_sel_hi:[1,0,1]
	v_pk_fma_f32 v[6:7], v[6:7], s[0:1], v[10:11] op_sel_hi:[1,0,1]
	v_cvt_pk_f32_fp8_e32 v[10:11], v8
	v_pk_fma_f32 v[10:11], v[10:11], s[0:1], v[14:15] op_sel_hi:[1,0,1]
	v_cvt_pk_f32_fp8_sdwa v[14:15], v8 src0_sel:WORD_1
	v_pk_fma_f32 v[14:15], v[14:15], s[0:1], v[18:19] op_sel_hi:[1,0,1]
	v_cvt_pk_f32_fp8_e32 v[18:19], v9
	v_cvt_pk_f32_fp8_sdwa v[8:9], v9 src0_sel:WORD_1
	v_pk_fma_f32 v[18:19], v[18:19], s[0:1], v[22:23] op_sel_hi:[1,0,1]
	v_pk_fma_f32 v[8:9], v[8:9], s[0:1], v[12:13] op_sel_hi:[1,0,1]
	s_waitcnt vmcnt(0)
	v_cvt_pk_f32_fp8_e32 v[12:13], v2
	v_readlane_b32 s0, v0, 15
	s_nop 1
	v_pk_fma_f32 v[184:185], v[12:13], s[0:1], v[16:17] op_sel_hi:[1,0,1]
	v_cvt_pk_f32_fp8_sdwa v[12:13], v2 src0_sel:WORD_1
	v_pk_fma_f32 v[186:187], v[12:13], s[0:1], v[20:21] op_sel_hi:[1,0,1]
	v_cvt_pk_f32_fp8_e32 v[12:13], v3
	v_cvt_pk_f32_fp8_sdwa v[2:3], v3 src0_sel:WORD_1
	v_pk_fma_f32 v[182:183], v[12:13], s[0:1], v[24:25] op_sel_hi:[1,0,1]
	v_pk_fma_f32 v[180:181], v[2:3], s[0:1], v[6:7] op_sel_hi:[1,0,1]
	v_cvt_pk_f32_fp8_e32 v[2:3], v4
	v_pk_fma_f32 v[178:179], v[2:3], s[0:1], v[10:11] op_sel_hi:[1,0,1]
	v_cvt_pk_f32_fp8_sdwa v[2:3], v4 src0_sel:WORD_1
	v_pk_fma_f32 v[176:177], v[2:3], s[0:1], v[14:15] op_sel_hi:[1,0,1]
	v_cvt_pk_f32_fp8_e32 v[2:3], v5
	v_pk_fma_f32 v[174:175], v[2:3], s[0:1], v[18:19] op_sel_hi:[1,0,1]
	v_cvt_pk_f32_fp8_sdwa v[2:3], v5 src0_sel:WORD_1
	v_pk_fma_f32 v[172:173], v[2:3], s[0:1], v[8:9] op_sel_hi:[1,0,1]
	s_add_i32 s1, s1, 64
	s_cmpk_lg_i32 s1, 0x200
	s_cbranch_scc1 .LBB0_870
	s_setprio 3
	v_add_u32_e32 v0, 0xfffff000, v152
	v_lshrrev_b32_e32 v0, 10, v0
	v_add_u32_e32 v0, 1, v0
	v_cmp_lt_i32_e32 vcc, s57, v152
	v_mov_b64_e32 v[2:3], s[16:17]
	v_lshlrev_b64 v[4:5], 12, v[152:153]
	v_cndmask_b32_e32 v0, 0, v0, vcc
	v_add_u32_e32 v46, s40, v0
	v_mad_u64_u32 v[2:3], s[0:1], v46, s63, v[2:3]
	v_lshlrev_b32_e32 v0, 2, v136
	v_lshl_add_u64 v[2:3], v[2:3], 0, v[0:1]
	s_mov_b64 s[0:1], 0x5000
	v_lshl_add_u64 v[52:53], v[2:3], 0, s[0:1]
	s_movk_i32 s0, 0x5000
	v_lshl_add_u64 v[40:41], v[142:143], 0, v[4:5]
	v_add_co_u32_e32 v2, vcc, s0, v2
	global_load_dwordx4 v[10:13], v[40:41], off
	s_nop 0
	v_addc_co_u32_e32 v3, vcc, 0, v3, vcc
	global_load_dwordx4 v[16:19], v[2:3], off
	s_nop 0
	global_load_dwordx4 v[2:5], v[146:147], off
	global_load_dwordx4 v[6:9], v[148:149], off
	v_lshlrev_b64 v[38:39], 10, v[152:153]
	s_mov_b64 s[0:1], -1
	s_waitcnt vmcnt(2)
	v_pk_mul_f32 v[14:15], v[184:185], v[16:17]
	s_nop 0
	v_pk_fma_f32 v[16:17], v[10:11], s[86:87], v[14:15] op_sel_hi:[1,0,1]
	s_nop 0
	v_add_f32_e32 v10, 0, v16
	v_add_f32_e32 v20, v17, v10
	v_pk_mul_f32 v[10:11], v[186:187], v[18:19]
	s_nop 0
	v_pk_fma_f32 v[14:15], v[12:13], s[86:87], v[10:11] op_sel_hi:[1,0,1]
	s_nop 0
	v_add_f32_e32 v10, v14, v20
	v_add_f32_e32 v30, v15, v10
	global_load_dwordx4 v[22:25], v[40:41], off offset:1024
	global_load_dwordx4 v[26:29], v[52:53], off offset:1024
	global_load_dwordx4 v[10:13], v[146:147], off offset:1024
	global_load_dwordx4 v[18:21], v[148:149], off offset:1024
	s_waitcnt vmcnt(2)
	v_pk_mul_f32 v[26:27], v[182:183], v[26:27]
	s_nop 0
	v_pk_fma_f32 v[44:45], v[22:23], s[86:87], v[26:27] op_sel_hi:[1,0,1]
	s_nop 0
	v_add_f32_e32 v22, v44, v30
	v_add_f32_e32 v26, v45, v22
	v_pk_mul_f32 v[22:23], v[180:181], v[28:29]
	s_nop 0
	v_pk_fma_f32 v[42:43], v[24:25], s[86:87], v[22:23] op_sel_hi:[1,0,1]
	s_nop 0
	v_add_f32_e32 v22, v42, v26
	v_add_f32_e32 v47, v43, v22
	global_load_dwordx4 v[30:33], v[40:41], off offset:2048
	global_load_dwordx4 v[34:37], v[52:53], off offset:2048
	global_load_dwordx4 v[22:25], v[146:147], off offset:2048
	global_load_dwordx4 v[26:29], v[148:149], off offset:2048
	s_waitcnt vmcnt(2)
	v_pk_mul_f32 v[34:35], v[178:179], v[34:35]
	s_nop 0
	v_pk_fma_f32 v[56:57], v[30:31], s[86:87], v[34:35] op_sel_hi:[1,0,1]
	s_nop 0
	v_add_f32_e32 v30, v56, v47
	v_add_f32_e32 v34, v57, v30
	v_pk_mul_f32 v[30:31], v[176:177], v[36:37]
	s_nop 0
	v_pk_fma_f32 v[58:59], v[32:33], s[86:87], v[30:31] op_sel_hi:[1,0,1]
	s_nop 0
	v_add_f32_e32 v30, v58, v34
	v_add_f32_e32 v47, v59, v30
	global_load_dwordx4 v[48:51], v[40:41], off offset:3072
	s_nop 0
	global_load_dwordx4 v[52:55], v[52:53], off offset:3072
	s_nop 0
	global_load_dwordx4 v[30:33], v[146:147], off offset:3072
	global_load_dwordx4 v[34:37], v[148:149], off offset:3072
	s_waitcnt vmcnt(2)
	v_pk_mul_f32 v[52:53], v[174:175], v[52:53]
	s_nop 0
	v_pk_fma_f32 v[48:49], v[48:49], s[86:87], v[52:53] op_sel_hi:[1,0,1]
	v_pk_mul_f32 v[52:53], v[172:173], v[54:55]
	v_add_f32_e32 v47, v48, v47
	v_add_f32_e32 v47, v49, v47
	v_pk_fma_f32 v[50:51], v[50:51], s[86:87], v[52:53] op_sel_hi:[1,0,1]
	s_nop 0
	v_add_f32_e32 v47, v50, v47
	v_add_f32_e32 v47, v51, v47
	ds_bpermute_b32 v52, v215, v47
	s_waitcnt lgkmcnt(0)
	v_add_f32_e32 v47, v47, v52
	ds_bpermute_b32 v52, v214, v47
	s_waitcnt lgkmcnt(0)
	v_add_f32_e32 v47, v47, v52
	s_waitcnt lgkmcnt(0)
	s_nop 1
	v_add_f32_dpp v47, v47, v47 row_ror:8 row_mask:0xf bank_mask:0xf
	s_waitcnt lgkmcnt(0)
	s_nop 1
	v_mov_b32_dpp v52, v47 row_half_mirror row_mask:0xf bank_mask:0xf
	s_nop 1
	v_add_f32_dpp v47, v52, v47 quad_perm:[3,2,1,0] row_mask:0xf bank_mask:0xf
	s_waitcnt lgkmcnt(0)
	s_nop 1
	v_add_f32_dpp v47, v47, v47 quad_perm:[2,3,0,1] row_mask:0xf bank_mask:0xf
	s_waitcnt lgkmcnt(0)
	s_nop 1
	v_add_f32_dpp v47, v47, v47 quad_perm:[1,0,3,2] row_mask:0xf bank_mask:0xf
	v_mul_f32_e32 v52, 0x3a800000, v47
	v_pk_add_f32 v[16:17], v[16:17], v[52:53] op_sel_hi:[1,0] neg_lo:[0,1] neg_hi:[0,1]
	v_pk_add_f32 v[60:61], v[14:15], v[52:53] op_sel_hi:[1,0] neg_lo:[0,1] neg_hi:[0,1]
	v_pk_mul_f32 v[54:55], v[16:17], v[16:17]
	v_pk_mul_f32 v[14:15], v[60:61], v[60:61]
	v_add_f32_e32 v47, v54, v55
	v_pk_add_f32 v[44:45], v[44:45], v[52:53] op_sel_hi:[1,0] neg_lo:[0,1] neg_hi:[0,1]
	v_add_f32_e32 v14, v14, v47
	v_pk_mul_f32 v[62:63], v[44:45], v[44:45]
	v_add_f32_e32 v14, v15, v14
	v_pk_add_f32 v[42:43], v[42:43], v[52:53] op_sel_hi:[1,0] neg_lo:[0,1] neg_hi:[0,1]
	v_add_f32_e32 v14, v62, v14
	v_pk_mul_f32 v[64:65], v[42:43], v[42:43]
	v_add_f32_e32 v14, v63, v14
	v_pk_add_f32 v[56:57], v[56:57], v[52:53] op_sel_hi:[1,0] neg_lo:[0,1] neg_hi:[0,1]
	v_add_f32_e32 v14, v64, v14
	v_pk_mul_f32 v[66:67], v[56:57], v[56:57]
	v_add_f32_e32 v14, v65, v14
	v_pk_add_f32 v[58:59], v[58:59], v[52:53] op_sel_hi:[1,0] neg_lo:[0,1] neg_hi:[0,1]
	v_add_f32_e32 v14, v66, v14
	v_pk_mul_f32 v[68:69], v[58:59], v[58:59]
	v_add_f32_e32 v14, v67, v14
	v_pk_add_f32 v[48:49], v[48:49], v[52:53] op_sel_hi:[1,0] neg_lo:[0,1] neg_hi:[0,1]
	v_add_f32_e32 v14, v68, v14
	v_pk_mul_f32 v[70:71], v[48:49], v[48:49]
	v_add_f32_e32 v14, v69, v14
	v_pk_add_f32 v[50:51], v[50:51], v[52:53] op_sel_hi:[1,0] neg_lo:[0,1] neg_hi:[0,1]
	v_add_f32_e32 v14, v70, v14
	v_pk_mul_f32 v[52:53], v[50:51], v[50:51]
	v_add_f32_e32 v14, v71, v14
	v_add_f32_e32 v14, v52, v14
	v_add_f32_e32 v14, v53, v14
	ds_bpermute_b32 v15, v215, v14
	s_waitcnt lgkmcnt(0)
	v_add_f32_e32 v14, v14, v15
	ds_bpermute_b32 v15, v214, v14
	s_waitcnt lgkmcnt(0)
	v_add_f32_e32 v14, v14, v15
	s_waitcnt lgkmcnt(0)
	s_nop 1
	v_add_f32_dpp v14, v14, v14 row_ror:8 row_mask:0xf bank_mask:0xf
	s_waitcnt lgkmcnt(0)
	s_nop 1
	v_mov_b32_dpp v15, v14 row_half_mirror row_mask:0xf bank_mask:0xf
	s_nop 1
	v_add_f32_dpp v14, v15, v14 quad_perm:[3,2,1,0] row_mask:0xf bank_mask:0xf
	s_waitcnt lgkmcnt(0)
	s_nop 1
	v_add_f32_dpp v14, v14, v14 quad_perm:[2,3,0,1] row_mask:0xf bank_mask:0xf
	s_waitcnt lgkmcnt(0)
	s_nop 1
	v_add_f32_dpp v14, v14, v14 quad_perm:[1,0,3,2] row_mask:0xf bank_mask:0xf
	v_fmamk_f32 v14, v14, 0x3a800000, v201
	v_cmp_gt_f32_e32 vcc, s62, v14
	v_mul_f32_e32 v15, 0x4b800000, v14
	s_nop 0
	v_cndmask_b32_e32 v14, v14, v15, vcc
	v_rsq_f32_e32 v14, v14
	s_nop 0
	v_mul_f32_e32 v15, 0x45800000, v14
	v_cndmask_b32_e32 v52, v14, v15, vcc
	v_pk_mul_f32 v[14:15], v[16:17], v[52:53] op_sel_hi:[1,0]
	s_and_b64 vcc, exec, s[30:31]
	v_pk_fma_f32 v[14:15], v[2:3], v[14:15], v[6:7]
	v_pk_mul_f32 v[2:3], v[60:61], v[52:53] op_sel_hi:[1,0]
	s_nop 0
	v_pk_fma_f32 v[16:17], v[4:5], v[2:3], v[8:9]
	v_pk_mul_f32 v[2:3], v[44:45], v[52:53] op_sel_hi:[1,0]
	v_pk_mul_f32 v[4:5], v[50:51], v[52:53] op_sel_hi:[1,0]
	v_pk_fma_f32 v[10:11], v[10:11], v[2:3], v[18:19]
	v_pk_mul_f32 v[2:3], v[42:43], v[52:53] op_sel_hi:[1,0]
	s_waitcnt vmcnt(0)
	v_pk_fma_f32 v[4:5], v[32:33], v[4:5], v[36:37]
	v_pk_fma_f32 v[12:13], v[12:13], v[2:3], v[20:21]
	v_pk_mul_f32 v[2:3], v[56:57], v[52:53] op_sel_hi:[1,0]
	s_nop 0
	v_pk_fma_f32 v[6:7], v[22:23], v[2:3], v[26:27]
	v_pk_mul_f32 v[2:3], v[58:59], v[52:53] op_sel_hi:[1,0]
	s_nop 0
	v_pk_fma_f32 v[8:9], v[24:25], v[2:3], v[28:29]
	v_pk_mul_f32 v[2:3], v[48:49], v[52:53] op_sel_hi:[1,0]
	s_nop 0
	v_pk_fma_f32 v[2:3], v[30:31], v[2:3], v[34:35]
	s_cbranch_vccz .LBB0_873
	v_add_f32_e32 v18, 0, v14
	v_add_f32_e32 v18, v15, v18
	v_add_f32_e32 v18, v16, v18
	v_add_f32_e32 v18, v17, v18
	v_add_f32_e32 v18, v10, v18
	v_add_f32_e32 v18, v11, v18
	v_add_f32_e32 v18, v12, v18
	v_add_f32_e32 v18, v13, v18
	v_add_f32_e32 v18, v6, v18
	v_add_f32_e32 v18, v7, v18
	v_add_f32_e32 v18, v8, v18
	v_add_f32_e32 v18, v9, v18
	v_add_f32_e32 v18, v2, v18
	v_add_f32_e32 v18, v3, v18
	v_add_f32_e32 v18, v4, v18
	v_add_f32_e32 v18, v5, v18
	ds_bpermute_b32 v19, v215, v18
	v_add_u32_e32 v22, 3, v46
	global_store_dwordx4 v[40:41], v[14:17], off
	global_store_dwordx4 v[40:41], v[10:13], off offset:1024
	s_waitcnt lgkmcnt(0)
	v_add_f32_e32 v20, v18, v19
	ds_bpermute_b32 v21, v214, v20
	v_mov_b64_e32 v[18:19], s[16:17]
	v_mad_u64_u32 v[18:19], s[0:1], v22, s63, v[18:19]
	v_lshl_add_u64 v[48:49], v[18:19], 0, v[0:1]
	s_waitcnt lgkmcnt(0)
	v_add_f32_e32 v20, v20, v21
	v_add_co_u32_e32 v18, vcc, s58, v48
	s_mov_b64 s[0:1], 0x1000
	s_nop 0
	v_addc_co_u32_e32 v19, vcc, 0, v49, vcc
	s_waitcnt lgkmcnt(0)
	s_nop 1
	v_add_f32_dpp v0, v20, v20 row_ror:8 row_mask:0xf bank_mask:0xf
	v_lshl_add_u64 v[30:31], v[48:49], 0, s[0:1]
	global_load_dwordx4 v[18:21], v[18:19], off
	s_nop 0
	global_load_dwordx4 v[22:25], v[30:31], off offset:1024
	s_nop 0
	global_store_dwordx4 v[40:41], v[6:9], off offset:2048
	global_store_dwordx4 v[40:41], v[2:5], off offset:3072
	s_mov_b64 s[0:1], 0
	s_waitcnt lgkmcnt(0)
	s_nop 1
	v_mov_b32_dpp v26, v0 row_half_mirror row_mask:0xf bank_mask:0xf
	s_nop 1
	v_add_f32_dpp v0, v26, v0 quad_perm:[3,2,1,0] row_mask:0xf bank_mask:0xf
	s_waitcnt lgkmcnt(0)
	s_nop 1
	v_add_f32_dpp v0, v0, v0 quad_perm:[2,3,0,1] row_mask:0xf bank_mask:0xf
	global_load_dwordx4 v[26:29], v[30:31], off offset:2048
	s_nop 0
	global_load_dwordx4 v[30:33], v[30:31], off offset:3072
	s_nop 0
	global_load_dwordx4 v[34:37], v[48:49], off
	global_load_dwordx4 v[40:43], v[48:49], off offset:1024
	s_waitcnt lgkmcnt(0)
	s_nop 1
	v_add_f32_dpp v0, v0, v0 quad_perm:[1,0,3,2] row_mask:0xf bank_mask:0xf
	global_load_dwordx4 v[44:47], v[48:49], off offset:2048
	v_mul_f32_e32 v0, 0x3a800000, v0
	global_load_dwordx4 v[48:51], v[48:49], off offset:3072
	v_pk_add_f32 v[54:55], v[14:15], v[0:1] op_sel_hi:[1,0] neg_lo:[0,1] neg_hi:[0,1]
	v_pk_add_f32 v[52:53], v[16:17], v[0:1] op_sel_hi:[1,0] neg_lo:[0,1] neg_hi:[0,1]
	v_pk_mul_f32 v[60:61], v[54:55], v[54:55]
	v_pk_add_f32 v[56:57], v[12:13], v[0:1] op_sel_hi:[1,0] neg_lo:[0,1] neg_hi:[0,1]
	v_pk_mul_f32 v[58:59], v[52:53], v[52:53]
	v_pk_add_f32 v[64:65], v[10:11], v[0:1] op_sel_hi:[1,0] neg_lo:[0,1] neg_hi:[0,1]
	v_pk_add_f32 v[68:69], v[8:9], v[0:1] op_sel_hi:[1,0] neg_lo:[0,1] neg_hi:[0,1]
	v_pk_add_f32 v[72:73], v[6:7], v[0:1] op_sel_hi:[1,0] neg_lo:[0,1] neg_hi:[0,1]
	v_pk_add_f32 v[76:77], v[4:5], v[0:1] op_sel_hi:[1,0] neg_lo:[0,1] neg_hi:[0,1]
	v_pk_add_f32 v[80:81], v[2:3], v[0:1] op_sel_hi:[1,0] neg_lo:[0,1] neg_hi:[0,1]
	v_add_f32_e32 v0, v60, v61
	v_add_f32_e32 v0, v58, v0
	v_pk_mul_f32 v[66:67], v[64:65], v[64:65]
	v_add_f32_e32 v0, v59, v0
	v_add_f32_e32 v0, v66, v0
	v_pk_mul_f32 v[62:63], v[56:57], v[56:57]
	v_add_f32_e32 v0, v67, v0
	v_add_f32_e32 v0, v62, v0
	v_pk_mul_f32 v[74:75], v[72:73], v[72:73]
	v_add_f32_e32 v0, v63, v0
	v_add_f32_e32 v0, v74, v0
	v_pk_mul_f32 v[70:71], v[68:69], v[68:69]
	v_add_f32_e32 v0, v75, v0
	v_add_f32_e32 v0, v70, v0
	v_pk_mul_f32 v[82:83], v[80:81], v[80:81]
	v_add_f32_e32 v0, v71, v0
	v_add_f32_e32 v0, v82, v0
	v_pk_mul_f32 v[78:79], v[76:77], v[76:77]
	v_add_f32_e32 v0, v83, v0
	v_add_f32_e32 v0, v78, v0
	v_add_f32_e32 v0, v79, v0
	ds_bpermute_b32 v58, v215, v0
	s_waitcnt lgkmcnt(0)
	v_add_f32_e32 v0, v0, v58
	ds_bpermute_b32 v58, v214, v0
	s_waitcnt lgkmcnt(0)
	v_add_f32_e32 v0, v0, v58
	s_waitcnt lgkmcnt(0)
	s_nop 1
	v_add_f32_dpp v0, v0, v0 row_ror:8 row_mask:0xf bank_mask:0xf
	s_waitcnt lgkmcnt(0)
	s_nop 1
	v_mov_b32_dpp v58, v0 row_half_mirror row_mask:0xf bank_mask:0xf
	s_nop 1
	v_add_f32_dpp v0, v58, v0 quad_perm:[3,2,1,0] row_mask:0xf bank_mask:0xf
	s_waitcnt lgkmcnt(0)
	s_nop 1
	v_add_f32_dpp v0, v0, v0 quad_perm:[2,3,0,1] row_mask:0xf bank_mask:0xf
	s_waitcnt vmcnt(9)
	v_pk_add_f32 v[18:19], v[18:19], 1.0 op_sel_hi:[1,0]
	v_pk_add_f32 v[20:21], v[20:21], 1.0 op_sel_hi:[1,0]
	s_waitcnt vmcnt(8)
	v_pk_add_f32 v[22:23], v[22:23], 1.0 op_sel_hi:[1,0]
	v_pk_add_f32 v[24:25], v[24:25], 1.0 op_sel_hi:[1,0]
	s_waitcnt lgkmcnt(0)
	s_nop 1
	v_add_f32_dpp v0, v0, v0 quad_perm:[1,0,3,2] row_mask:0xf bank_mask:0xf
	v_fmamk_f32 v0, v0, 0x3a800000, v201
	v_mul_f32_e32 v58, 0x4b800000, v0
	v_cmp_gt_f32_e32 vcc, s62, v0
	s_waitcnt vmcnt(5)
	v_pk_add_f32 v[28:29], v[28:29], 1.0 op_sel_hi:[1,0]
	s_waitcnt vmcnt(4)
	v_pk_add_f32 v[30:31], v[30:31], 1.0 op_sel_hi:[1,0]
	v_cndmask_b32_e32 v0, v0, v58, vcc
	v_rsq_f32_e32 v0, v0
	v_pk_add_f32 v[32:33], v[32:33], 1.0 op_sel_hi:[1,0]
	v_pk_add_f32 v[26:27], v[26:27], 1.0 op_sel_hi:[1,0]
	v_mul_f32_e32 v58, 0x45800000, v0
	v_cndmask_b32_e32 v0, v0, v58, vcc
	v_pk_mul_f32 v[54:55], v[54:55], v[0:1] op_sel_hi:[1,0]
	v_pk_mul_f32 v[52:53], v[52:53], v[0:1] op_sel_hi:[1,0]
	s_waitcnt vmcnt(3)
	v_pk_fma_f32 v[18:19], v[18:19], v[54:55], v[34:35]
	v_pk_mul_f32 v[34:35], v[68:69], v[0:1] op_sel_hi:[1,0]
	v_pk_mul_f32 v[58:59], v[64:65], v[0:1] op_sel_hi:[1,0]
	s_waitcnt vmcnt(1)
	v_pk_fma_f32 v[28:29], v[34:35], v[28:29], v[46:47]
	v_pk_mul_f32 v[34:35], v[80:81], v[0:1] op_sel_hi:[1,0]
	v_pk_mul_f32 v[56:57], v[56:57], v[0:1] op_sel_hi:[1,0]
	v_pk_fma_f32 v[20:21], v[20:21], v[52:53], v[36:37]
	s_waitcnt vmcnt(0)
	v_pk_fma_f32 v[30:31], v[34:35], v[30:31], v[48:49]
	v_pk_mul_f32 v[34:35], v[76:77], v[0:1] op_sel_hi:[1,0]
	v_pk_mul_f32 v[60:61], v[72:73], v[0:1] op_sel_hi:[1,0]
	v_pk_fma_f32 v[22:23], v[22:23], v[58:59], v[40:41]
	v_pk_fma_f32 v[24:25], v[24:25], v[56:57], v[42:43]
	v_pk_fma_f32 v[32:33], v[34:35], v[32:33], v[50:51]
	v_lshl_add_u64 v[34:35], v[38:39], 1, v[138:139]
	v_cvt_pk_bf16_f32 v18, v18, v19
	v_cvt_pk_bf16_f32 v19, v20, v21
	v_pk_fma_f32 v[26:27], v[26:27], v[60:61], v[44:45]
	global_store_dwordx2 v[34:35], v[18:19], off
	v_cvt_pk_bf16_f32 v18, v22, v23
	v_cvt_pk_bf16_f32 v19, v24, v25
	global_store_dwordx2 v[34:35], v[18:19], off offset:512
	v_cvt_pk_bf16_f32 v18, v26, v27
	v_cvt_pk_bf16_f32 v19, v28, v29
	global_store_dwordx2 v[34:35], v[18:19], off offset:1024
	v_cvt_pk_bf16_f32 v18, v30, v31
	v_cvt_pk_bf16_f32 v19, v32, v33
	global_store_dwordx2 v[34:35], v[18:19], off offset:1536
